# v34 + packed v_pk_mul_f32 in the HGRN MFMA chunk loop split into scalar v_mul_f32 pairs (bit-identical)
# speedup vs baseline: 1.0034x; 1.0015x over previous
; #define LAS __attribute__((address_space(3)))
; __device__ __forceinline__ unsigned pk2(float lo, float hi) { f32x2_t v = {lo, hi}; bf16x2_t b = __builtin_convertvector(v, bf16x2_t); return __builtin_bit_cast(unsigned, b); }
; __device__ __forceinline__ float fast_exp2(float x) { return __builtin_amdgcn_exp2f(x); }
; __device__ __forceinline__ void hm_stage(LAS unsigned char* wl, const unsigned (&rq)[16], const unsigned (&rz)[16], const unsigned (&rv)[16], float oml, int lane) {
;     float kt[16]; float run = 1.0f;
;     unsigned vpk[8];
; #pragma unroll
;     for (int i = 0; i < 16; ++i) {
;         const float z = bf2f(rz[i]), q = bf2f(rq[i]);
;         const float sg = __builtin_amdgcn_rcpf(1.0f + fast_exp2(z * LOG2E));
;         const float k = oml * sg;
;         run = fmaxf(run * (1.0f - k), 8.673617379884035e-19f);
;         const float ieb = __builtin_amdgcn_rcpf(run);
;         kt[i] = k * ieb;
;         *(LAS unsigned short*)(wl + HM_QT + i * HM_QP + lane * 2) = (unsigned short)pk2(q * run, 0.f);
;         *(LAS unsigned short*)(wl + HM_KT + i * HM_QP + lane * 2) = (unsigned short)pk2(kt[i], 0.f);
;         if (i & 1) vpk[i >> 1] = rv[i - 1] | (rv[i] << 16);
;     }
.LBB0_465:
	s_waitcnt vmcnt(48)
	v_lshlrev_b32_e32 v64, 16, v151
	v_mul_f32_e32 v64, 0x3fb8aa3b, v64
	v_exp_f32_e32 v64, v64
	v_lshlrev_b32_e32 v89, 16, v149
	v_lshlrev_b32_e32 v90, 16, v148
	v_lshlrev_b32_e32 v91, 16, v147
	v_add_f32_e32 v64, 1.0, v64
	v_rcp_f32_e32 v74, v64
	v_lshlrev_b32_e32 v64, 16, v150
	v_mul_f32_e32 v64, 0x3fb8aa3b, v64
	v_exp_f32_e32 v64, v64
	v_lshlrev_b32_e32 v92, 16, v155
	v_lshlrev_b32_e32 v93, 16, v154
	v_lshlrev_b32_e32 v94, 16, v164
	v_add_f32_e32 v64, 1.0, v64
	v_rcp_f32_e32 v75, v64
	v_lshlrev_b32_e32 v64, 16, v158
	v_mul_f32_e32 v64, 0x3fb8aa3b, v64
	v_exp_f32_e32 v64, v64
	v_mul_f32_e32 v74, v136, v74
	v_mul_f32_e32 v75, v137, v75
	v_lshlrev_b32_e32 v95, 16, v163
	v_sub_f32_e32 v88, 1.0, v74
	v_max_f32_e32 v119, 0x21800000, v88
	v_add_f32_e32 v64, 1.0, v64
	v_mul_f32_e32 v89, v119, v89
	v_rcp_f32_e32 v78, v64
	v_lshlrev_b32_e32 v64, 16, v157
	v_cvt_pk_bf16_f32 v89, v89, s0
	v_mul_f32_e32 v64, 0x3fb8aa3b, v64
	ds_write_b16 v139, v89
	v_sub_f32_e32 v89, 1.0, v75
	v_exp_f32_e32 v64, v64
	v_mul_f32_e32 v89, v89, v119
	v_rcp_f32_e32 v88, v119
	v_max_f32_e32 v119, 0x21800000, v89
	v_rcp_f32_e32 v89, v119
	v_add_f32_e32 v64, 1.0, v64
	v_rcp_f32_e32 v79, v64
	v_lshlrev_b32_e32 v64, 16, v156
	v_mul_f32_e32 v64, 0x3fb8aa3b, v64
	v_mul_f32_e32 v74, v74, v88
	v_mul_f32_e32 v75, v75, v89
	v_exp_f32_e32 v64, v64
	v_cvt_pk_bf16_f32 v88, v74, s0
	ds_write_b16 v139, v88 offset:2304
	v_mul_f32_e32 v88, v119, v90
	v_mul_f32_e32 v78, v136, v78
	v_mul_f32_e32 v79, v137, v79
	v_cvt_pk_bf16_f32 v88, v88, s0
	v_sub_f32_e32 v117, 1.0, v78
	ds_write_b16 v139, v88 offset:144
	v_cvt_pk_bf16_f32 v88, v75, s0
	v_add_f32_e32 v64, 1.0, v64
	ds_write_b16 v139, v88 offset:2448
	v_mul_f32_e32 v88, v117, v119
	v_rcp_f32_e32 v82, v64
	v_lshlrev_b32_e32 v64, 16, v166
	v_max_f32_e32 v89, 0x21800000, v88
	v_mul_f32_e32 v64, 0x3fb8aa3b, v64
	v_sub_f32_e32 v118, 1.0, v79
	v_mul_f32_e32 v90, v89, v91
	v_exp_f32_e32 v64, v64
	v_rcp_f32_e32 v88, v89
	v_cvt_pk_bf16_f32 v90, v90, s0
	v_mul_f32_e32 v89, v118, v89
	ds_write_b16 v139, v90 offset:288
	v_max_f32_e32 v90, 0x21800000, v89
	v_rcp_f32_e32 v89, v90
	v_add_f32_e32 v64, 1.0, v64
	v_rcp_f32_e32 v83, v64
	v_lshlrev_b32_e32 v64, 16, v165
	v_mul_f32_e32 v64, 0x3fb8aa3b, v64
	v_mul_f32_e32 v78, v78, v88
	v_mul_f32_e32 v79, v79, v89
	v_exp_f32_e32 v64, v64
	v_cvt_pk_bf16_f32 v88, v78, s0
	ds_write_b16 v139, v88 offset:2592
	v_mul_f32_e32 v88, v90, v92
	v_mul_f32_e32 v82, v136, v82
	v_mul_f32_e32 v83, v137, v83
	v_cvt_pk_bf16_f32 v88, v88, s0
	v_sub_f32_e32 v115, 1.0, v82
	ds_write_b16 v139, v88 offset:432
	v_cvt_pk_bf16_f32 v88, v79, s0
	v_add_f32_e32 v64, 1.0, v64
	ds_write_b16 v139, v88 offset:2736
	v_mul_f32_e32 v88, v115, v90
	v_rcp_f32_e32 v84, v64
	v_lshlrev_b32_e32 v64, 16, v175
	v_max_f32_e32 v89, 0x21800000, v88
	v_mul_f32_e32 v64, 0x3fb8aa3b, v64
	v_sub_f32_e32 v116, 1.0, v83
	v_mul_f32_e32 v90, v89, v93
	v_exp_f32_e32 v64, v64
	v_rcp_f32_e32 v88, v89
	v_cvt_pk_bf16_f32 v90, v90, s0
	v_mul_f32_e32 v89, v116, v89
	ds_write_b16 v139, v90 offset:576
	v_max_f32_e32 v90, 0x21800000, v89
	v_rcp_f32_e32 v89, v90
	v_add_f32_e32 v64, 1.0, v64
	v_rcp_f32_e32 v85, v64
	v_lshlrev_b32_e32 v64, 16, v174
	v_mul_f32_e32 v64, 0x3fb8aa3b, v64
	v_mul_f32_e32 v82, v82, v88
	v_mul_f32_e32 v83, v83, v89
	v_exp_f32_e32 v64, v64
	v_cvt_pk_bf16_f32 v88, v82, s0
	ds_write_b16 v139, v88 offset:2880
	v_mul_f32_e32 v88, v90, v94
	v_mul_f32_e32 v84, v136, v84
	v_mul_f32_e32 v85, v137, v85
	v_cvt_pk_bf16_f32 v88, v88, s0
	v_sub_f32_e32 v113, 1.0, v84
	ds_write_b16 v139, v88 offset:720
	v_cvt_pk_bf16_f32 v88, v83, s0
	v_add_f32_e32 v64, 1.0, v64
	ds_write_b16 v139, v88 offset:3024
	v_mul_f32_e32 v88, v113, v90
	v_rcp_f32_e32 v86, v64
	v_lshlrev_b32_e32 v64, 16, v173
	v_max_f32_e32 v89, 0x21800000, v88
	v_mul_f32_e32 v64, 0x3fb8aa3b, v64
	v_sub_f32_e32 v114, 1.0, v85
	v_mul_f32_e32 v90, v89, v95
	v_exp_f32_e32 v64, v64
	v_rcp_f32_e32 v88, v89
	v_cvt_pk_bf16_f32 v90, v90, s0
	v_mul_f32_e32 v89, v114, v89
	ds_write_b16 v139, v90 offset:864
	v_max_f32_e32 v90, 0x21800000, v89
	v_rcp_f32_e32 v89, v90
	v_add_f32_e32 v64, 1.0, v64
	v_rcp_f32_e32 v87, v64
	v_lshlrev_b32_e32 v64, 16, v190
	v_mul_f32_e32 v64, 0x3fb8aa3b, v64
	v_mul_f32_e32 v84, v84, v88
	v_mul_f32_e32 v85, v85, v89
	v_lshlrev_b32_e32 v96, 16, v162
	v_exp_f32_e32 v64, v64
	v_cvt_pk_bf16_f32 v88, v84, s0
	ds_write_b16 v139, v88 offset:3168
	v_mul_f32_e32 v88, v90, v96
	v_mul_f32_e32 v86, v136, v86
	v_mul_f32_e32 v87, v137, v87
	v_cvt_pk_bf16_f32 v88, v88, s0
	v_sub_f32_e32 v111, 1.0, v86
	ds_write_b16 v139, v88 offset:1008
	v_cvt_pk_bf16_f32 v88, v85, s0
	v_add_f32_e32 v64, 1.0, v64
	ds_write_b16 v139, v88 offset:3312
	v_mul_f32_e32 v88, v111, v90
	v_lshlrev_b32_e32 v97, 16, v172
	v_rcp_f32_e32 v80, v64
	v_lshlrev_b32_e32 v64, 16, v189
	v_max_f32_e32 v89, 0x21800000, v88
	v_mul_f32_e32 v64, 0x3fb8aa3b, v64
	v_sub_f32_e32 v112, 1.0, v87
	v_mul_f32_e32 v90, v89, v97
	v_exp_f32_e32 v64, v64
	v_rcp_f32_e32 v88, v89
	v_cvt_pk_bf16_f32 v90, v90, s0
; #define LAS __attribute__((address_space(3)))
; __device__ __forceinline__ unsigned pk2(float lo, float hi) { f32x2_t v = {lo, hi}; bf16x2_t b = __builtin_convertvector(v, bf16x2_t); return __builtin_bit_cast(unsigned, b); }
; #define HM_LOAD(RQ, RZ, RV, j_) do { _Pragma("unroll") for (int i = 0; i < 16; ++i) { const bf16_t* pr_ = proj + HM_TOK((j_) * 16 + i) * INW; RQ[i] = pr_[qc]; RZ[i] = pr_[zc]; RV[i] = pr_[vc]; } } while (0)
; __device__ __forceinline__ void hm_stage(LAS unsigned char* wl, const unsigned (&rq)[16], const unsigned (&rz)[16], const unsigned (&rv)[16], float oml, int lane) {
;     ...
;     const float eB = run;
;     *(LAS float*)(wl + HM_EB + lane * 4) = eB;
;     u32x4 w0, w1;
;     w0.x = pk2(kt[0] * eB, kt[1] * eB); w0.y = pk2(kt[2] * eB, kt[3] * eB); w0.z = pk2(kt[4] * eB, kt[5] * eB); w0.w = pk2(kt[6] * eB, kt[7] * eB);
;     w1.x = pk2(kt[8] * eB, kt[9] * eB); w1.y = pk2(kt[10] * eB, kt[11] * eB); w1.z = pk2(kt[12] * eB, kt[13] * eB); w1.w = pk2(kt[14] * eB, kt[15] * eB);
;     *(LAS u32x4*)(wl + HM_KD + lane * 32) = w0; *(LAS u32x4*)(wl + HM_KD + lane * 32 + 16) = w1;
;     *(LAS u32x4*)(wl + HM_VT + lane * 32) = (u32x4){vpk[0], vpk[1], vpk[2], vpk[3]}; *(LAS u32x4*)(wl + HM_VT + lane * 32 + 16) = (u32x4){vpk[4], vpk[5], vpk[6], vpk[7]};
; __device__ __forceinline__ void hgrn_mfma_unit(const Params& P, int l, LAS unsigned char* lds, int b, int half) {
;     ...
;         for (int j = 0; j < NSC; j += 2) {
;             hm_stage(wl, aq, az, av, oml, lane);
;             if (j + 2 < NSC) HM_LOAD(aq, az, av, j + 2);
	v_mul_f32_e32 v89, v112, v89
	ds_write_b16 v139, v90 offset:1152
	v_max_f32_e32 v90, 0x21800000, v89
	v_rcp_f32_e32 v89, v90
	v_add_f32_e32 v64, 1.0, v64
	v_rcp_f32_e32 v81, v64
	v_lshlrev_b32_e32 v64, 16, v188
	v_mul_f32_e32 v64, 0x3fb8aa3b, v64
	v_mul_f32_e32 v86, v86, v88
	v_mul_f32_e32 v87, v87, v89
	v_lshlrev_b32_e32 v98, 16, v171
	v_exp_f32_e32 v64, v64
	v_cvt_pk_bf16_f32 v88, v86, s0
	ds_write_b16 v139, v88 offset:3456
	v_mul_f32_e32 v88, v90, v98
	v_mul_f32_e32 v80, v136, v80
	v_mul_f32_e32 v81, v137, v81
	v_cvt_pk_bf16_f32 v88, v88, s0
	v_sub_f32_e32 v109, 1.0, v80
	ds_write_b16 v139, v88 offset:1296
	v_cvt_pk_bf16_f32 v88, v87, s0
	v_add_f32_e32 v64, 1.0, v64
	ds_write_b16 v139, v88 offset:3600
	v_mul_f32_e32 v88, v109, v90
	v_lshlrev_b32_e32 v99, 16, v170
	v_rcp_f32_e32 v76, v64
	v_lshlrev_b32_e32 v64, 16, v198
	v_max_f32_e32 v89, 0x21800000, v88
	v_mul_f32_e32 v64, 0x3fb8aa3b, v64
	v_sub_f32_e32 v110, 1.0, v81
	v_mul_f32_e32 v90, v89, v99
	v_exp_f32_e32 v64, v64
	v_rcp_f32_e32 v88, v89
	v_cvt_pk_bf16_f32 v90, v90, s0
	v_mul_f32_e32 v89, v110, v89
	ds_write_b16 v139, v90 offset:1440
	v_max_f32_e32 v90, 0x21800000, v89
	v_rcp_f32_e32 v89, v90
	v_add_f32_e32 v64, 1.0, v64
	v_rcp_f32_e32 v77, v64
	v_lshlrev_b32_e32 v64, 16, v197
	v_mul_f32_e32 v64, 0x3fb8aa3b, v64
	v_mul_f32_e32 v80, v80, v88
	v_mul_f32_e32 v81, v81, v89
	v_lshlrev_b32_e32 v100, 16, v187
	v_exp_f32_e32 v64, v64
	v_cvt_pk_bf16_f32 v88, v80, s0
	ds_write_b16 v139, v88 offset:3744
	v_mul_f32_e32 v88, v90, v100
	v_mul_f32_e32 v76, v136, v76
	v_mul_f32_e32 v77, v137, v77
	v_cvt_pk_bf16_f32 v88, v88, s0
	v_sub_f32_e32 v107, 1.0, v76
	ds_write_b16 v139, v88 offset:1584
	v_cvt_pk_bf16_f32 v88, v81, s0
	v_add_f32_e32 v64, 1.0, v64
	ds_write_b16 v139, v88 offset:3888
	v_mul_f32_e32 v88, v107, v90
	v_lshlrev_b32_e32 v101, 16, v186
	v_rcp_f32_e32 v72, v64
	v_lshlrev_b32_e32 v64, 16, v211
	v_max_f32_e32 v89, 0x21800000, v88
	v_mul_f32_e32 v64, 0x3fb8aa3b, v64
	v_sub_f32_e32 v108, 1.0, v77
	v_mul_f32_e32 v90, v89, v101
	v_exp_f32_e32 v64, v64
	v_rcp_f32_e32 v88, v89
	v_cvt_pk_bf16_f32 v90, v90, s0
	v_mul_f32_e32 v89, v108, v89
	ds_write_b16 v139, v90 offset:1728
	v_max_f32_e32 v90, 0x21800000, v89
	v_rcp_f32_e32 v89, v90
	v_add_f32_e32 v64, 1.0, v64
	v_rcp_f32_e32 v73, v64
	v_lshlrev_b32_e32 v102, 16, v196
	v_mul_f32_e32 v88, v76, v88
	v_mul_f32_e32 v89, v77, v89
	v_lshlrev_b32_e32 v103, 16, v195
	v_cvt_pk_bf16_f32 v76, v88, s0
	ds_write_b16 v139, v76 offset:4032
	v_mul_f32_e32 v76, v90, v102
	v_mul_f32_e32 v72, v136, v72
	v_mul_f32_e32 v73, v137, v73
	v_cvt_pk_bf16_f32 v76, v76, s0
	v_sub_f32_e32 v105, 1.0, v72
	ds_write_b16 v139, v76 offset:1872
	v_cvt_pk_bf16_f32 v76, v89, s0
	ds_write_b16 v139, v76 offset:4176
	v_mul_f32_e32 v76, v105, v90
	v_max_f32_e32 v77, 0x21800000, v76
	v_sub_f32_e32 v106, 1.0, v73
	v_mul_f32_e32 v90, v77, v103
	v_rcp_f32_e32 v76, v77
	v_cvt_pk_bf16_f32 v90, v90, s0
	v_mul_f32_e32 v77, v106, v77
	ds_write_b16 v139, v90 offset:2016
	v_max_f32_e32 v90, 0x21800000, v77
	v_rcp_f32_e32 v77, v90
	v_lshlrev_b32_e32 v104, 16, v194
	s_add_i32 s28, s9, 2
	s_cmpk_gt_u32 s9, 0x8d
	v_mul_f32_e32 v92, v72, v76
	v_mul_f32_e32 v93, v73, v77
	v_mul_f32_e32 v76, v84, v90
	v_mul_f32_e32 v77, v85, v90
	v_cvt_pk_bf16_f32 v72, v92, s0
	ds_write_b16 v139, v72 offset:4320
	v_mul_f32_e32 v72, v90, v104
	v_cvt_pk_bf16_f32 v72, v72, s0
	ds_write_b16 v139, v72 offset:2160
	v_cvt_pk_bf16_f32 v72, v93, s0
	ds_write_b16 v139, v72 offset:4464
	v_mul_f32_e32 v72, v74, v90
	v_mul_f32_e32 v73, v75, v90
	v_mul_f32_e32 v74, v78, v90
	v_mul_f32_e32 v75, v79, v90
	v_cvt_pk_bf16_f32 v72, v72, v73
	v_cvt_pk_bf16_f32 v73, v74, v75
	v_mul_f32_e32 v74, v82, v90
	v_mul_f32_e32 v75, v83, v90
	v_mul_f32_e32 v78, v80, v90
	v_mul_f32_e32 v79, v81, v90
	v_cvt_pk_bf16_f32 v74, v74, v75
	v_cvt_pk_bf16_f32 v75, v76, v77
	v_mul_f32_e32 v76, v86, v90
	v_mul_f32_e32 v77, v87, v90
	s_cselect_b64 s[50:51], -1, 0
	v_add_u32_e32 v207, v133, v132
	v_cvt_pk_bf16_f32 v76, v76, v77
	v_cvt_pk_bf16_f32 v77, v78, v79
	v_mul_f32_e32 v78, v88, v90
	v_mul_f32_e32 v79, v89, v90
	v_mul_f32_e32 v80, v92, v90
	v_mul_f32_e32 v81, v93, v90
	s_and_b64 vcc, exec, s[50:51]
	v_lshl_or_b32 v64, v152, 16, v153
	v_lshl_or_b32 v65, v160, 16, v161
	v_lshl_or_b32 v66, v169, 16, v159
	v_lshl_or_b32 v67, v167, 16, v168
	v_lshl_or_b32 v68, v176, 16, v177
	v_lshl_or_b32 v69, v192, 16, v193
	v_lshl_or_b32 v70, v210, 16, v191
	v_lshl_or_b32 v71, v199, 16, v209
	ds_write_b32 v207, v90 offset:8704
	v_cvt_pk_bf16_f32 v78, v78, v79
	v_cvt_pk_bf16_f32 v79, v80, v81
	ds_write_b128 v146, v[72:75] offset:4608
	ds_write_b128 v146, v[76:79] offset:4624
	ds_write_b128 v146, v[64:67] offset:6656
	ds_write_b128 v146, v[68:71] offset:6672
	s_cbranch_vccnz .Lhm_a_skip
	s_lshl_b32 s12, s28, 4
	s_mov_b32 s18, 0x1600
	s_mov_b32 s19, 0
	s_cmp_eq_u64 s[38:39], 0
	s_cbranch_scc1 .Lhm_a_go
	s_cmp_lt_u32 s28, 16
	s_movk_i32 s13, 0x9ff
	s_cselect_b32 s13, 0xff, s13
	s_sub_u32 s12, s13, s12
	s_mov_b32 s18, 0xffffea00
	s_mov_b32 s19, -1

; #define LAS __attribute__((address_space(3)))
; __device__ __forceinline__ void hm_mfma(const LAS unsigned char* wl, f32x4 (&S)[4][4], f32x4 (&o)[4], int c16, int g) {
;     const bf16x8 zero8 = {0, 0, 0, 0, 0, 0, 0, 0};
;     f32x4 sc = (f32x4){0.f, 0.f, 0.f, 0.f};
; #pragma unroll
;     for (int kk = 0; kk < 2; ++kk) {
;         const bf16x8 a = *(const LAS bf16x8*)(wl + HM_KT + c16 * HM_QP + (32 * kk + 8 * g) * 2);
;         const bf16x8 bq = *(const LAS bf16x8*)(wl + HM_QT + c16 * HM_QP + (32 * kk + 8 * g) * 2);
;         sc = __builtin_amdgcn_mfma_f32_16x16x32_bf16(a, bq, sc, 0, 0, 0);
;     }
; #pragma unroll
;     for (int r = 0; r < 4; ++r) if (4 * g + r > c16) sc[r] = 0.f;
;     bf16x8 pb; { u32x4 w; w.x = pk2(sc[0], sc[1]); w.y = pk2(sc[2], sc[3]); w.z = 0u; w.w = 0u; pb = __builtin_bit_cast(bf16x8, w); }
;     bf16x8 qb[2];
; #pragma unroll
;     for (int kk = 0; kk < 2; ++kk) {
;         const u32x2 lo = *(const LAS u32x2*)(wl + HM_QT + c16 * HM_QP + (32 * kk + 4 * g) * 2), hi2 = *(const LAS u32x2*)(wl + HM_QT + c16 * HM_QP + (32 * kk + 16 + 4 * g) * 2);
;         qb[kk] = __builtin_bit_cast(bf16x8, ((u32x4){lo.x, lo.y, hi2.x, hi2.y}));
;     }
; #pragma unroll
;     for (int eb = 0; eb < 4; ++eb) {
;         const u32x2 va = *(const LAS u32x2*)(wl + HM_VT + (16 * eb + c16) * 32 + 8 * g);
;         const bf16x8 a = __builtin_bit_cast(bf16x8, ((u32x4){va.x, va.y, 0u, 0u}));
;         f32x4 acc = __builtin_amdgcn_mfma_f32_16x16x32_bf16(a, pb, (f32x4){0.f, 0.f, 0.f, 0.f}, 0, 0, 0);
; #pragma unroll
;         for (int kk = 0; kk < 2; ++kk) {
;             const f32x4 s0 = S[2 * kk][eb], s1 = S[2 * kk + 1][eb];
;             u32x4 w; w.x = pk2(s0[0], s0[1]); w.y = pk2(s0[2], s0[3]); w.z = pk2(s1[0], s1[1]); w.w = pk2(s1[2], s1[3]);
;             acc = __builtin_amdgcn_mfma_f32_16x16x32_bf16(__builtin_bit_cast(bf16x8, w), qb[kk], acc, 0, 0, 0);
;         }
;         o[eb] = acc;
;     }
;     bf16x8 af[4], bf[4]; f32x4 e4[4];
; #pragma unroll
;     for (int x = 0; x < 4; ++x) {
;         af[x] = (g < 2) ? *(const LAS bf16x8*)(wl + HM_KD + (16 * x + c16) * 32 + 16 * g) : zero8;
;         bf[x] = (g < 2) ? *(const LAS bf16x8*)(wl + HM_VT + (16 * x + c16) * 32 + 16 * g) : zero8;
;         e4[x] = *(const LAS f32x4*)(wl + HM_EB + (16 * x + 4 * g) * 4);
;     }
.LBB0_563:
	v_add_u32_e32 v183, v143, v138
	ds_read_b128 v[64:67], v183 offset:2304
	ds_read_b128 v[70:73], v183
	ds_read_b128 v[74:77], v183 offset:2368
	ds_read_b128 v[86:89], v183 offset:64
	v_add_u32_e32 v124, v145, v144
	ds_read2st64_b64 v[82:85], v124 offset0:13 offset1:14
	ds_read2st64_b64 v[90:93], v124 offset0:15 offset1:16
	v_mov_b32_e32 v80, v129
	v_mov_b32_e32 v81, v129
	v_mov_b32_e32 v68, s65
	s_waitcnt lgkmcnt(4)
	v_mfma_f32_16x16x32_bf16 v[64:67], v[64:67], v[70:73], 0
	s_waitcnt lgkmcnt(1)
	v_mov_b32_e32 v78, v82
	v_mov_b32_e32 v79, v83
	v_add_u32_e32 v125, v143, v144
	v_mfma_f32_16x16x32_bf16 v[64:67], v[74:77], v[86:89], v[64:67]
	v_mov_b32_e32 v128, v129
	v_cvt_pk_bf16_f32 v72, v60, v61
	v_cvt_pk_bf16_f32 v73, v62, v63
	v_cvt_pk_bf16_f32 v74, v44, v45
	v_cvt_pk_bf16_f32 v75, v46, v47
	s_nop 2
	v_cndmask_b32_e64 v68, v64, v68, s[40:41]
	v_cndmask_b32_e64 v65, 0, v65, s[42:43]
	v_cndmask_b32_e64 v66, v66, 0, s[44:45]
	v_cndmask_b32_e64 v67, v67, 0, s[46:47]
	v_cndmask_b32_e64 v64, v68, v64, s[42:43]
	v_cvt_pk_bf16_f32 v126, v64, v65
	v_cvt_pk_bf16_f32 v127, v66, v67
	ds_read2_b64 v[64:67], v125 offset1:4
	v_cvt_pk_bf16_f32 v76, v56, v57
	v_mfma_f32_16x16x32_bf16 v[68:71], v[78:81], v[126:129], 0
	ds_read2_b64 v[80:83], v125 offset0:8 offset1:12
	v_cvt_pk_bf16_f32 v77, v58, v59
	v_cvt_pk_bf16_f32 v78, v40, v41
	s_waitcnt lgkmcnt(1)
	v_mfma_f32_16x16x32_bf16 v[68:71], v[72:75], v[64:67], v[68:71]
	v_cvt_pk_bf16_f32 v72, v28, v29
	v_cvt_pk_bf16_f32 v73, v30, v31
	v_cvt_pk_bf16_f32 v74, v12, v13
	v_cvt_pk_bf16_f32 v75, v14, v15
	v_cvt_pk_bf16_f32 v79, v42, v43
	v_cvt_pk_bf16_f32 v86, v36, v37
	s_waitcnt lgkmcnt(0)
	v_mfma_f32_16x16x32_bf16 v[68:71], v[72:75], v[80:83], v[68:71]
	v_mov_b32_e32 v72, v84
	v_mov_b32_e32 v73, v85
	v_mov_b32_e32 v74, v129
	v_mov_b32_e32 v75, v129
	v_cvt_pk_bf16_f32 v84, v52, v53
	v_cvt_pk_bf16_f32 v85, v54, v55
	v_mfma_f32_16x16x32_bf16 v[72:75], v[72:75], v[126:129], 0
	v_cvt_pk_bf16_f32 v87, v38, v39
	v_cvt_pk_bf16_f32 v88, v48, v49
	v_cvt_pk_bf16_f32 v89, v50, v51
	v_mfma_f32_16x16x32_bf16 v[72:75], v[76:79], v[64:67], v[72:75]
	v_cvt_pk_bf16_f32 v76, v24, v25
	v_cvt_pk_bf16_f32 v77, v26, v27
	v_cvt_pk_bf16_f32 v78, v8, v9
	v_cvt_pk_bf16_f32 v79, v10, v11
	v_add_u32_e32 v182, v145, v138
	v_mov_b32_e32 v94, 0
	v_mfma_f32_16x16x32_bf16 v[72:75], v[76:79], v[80:83], v[72:75]
	v_mov_b32_e32 v76, v90
	v_mov_b32_e32 v77, v91
	v_mov_b32_e32 v78, v129
	v_mov_b32_e32 v79, v129
	v_cvt_pk_bf16_f32 v90, v32, v33
	v_cvt_pk_bf16_f32 v91, v34, v35
	v_mfma_f32_16x16x32_bf16 v[76:79], v[76:79], v[126:129], 0
	v_mov_b32_e32 v95, 0
	v_mfma_f32_16x16x32_bf16 v[76:79], v[84:87], v[64:67], v[76:79]
	v_cvt_pk_bf16_f32 v84, v20, v21
	v_cvt_pk_bf16_f32 v85, v22, v23
	v_cvt_pk_bf16_f32 v86, v4, v5
	v_cvt_pk_bf16_f32 v87, v6, v7
	s_nop 1
	v_mfma_f32_16x16x32_bf16 v[76:79], v[84:87], v[80:83], v[76:79]
	v_mov_b32_e32 v84, v92
	v_mov_b32_e32 v85, v93
	v_mov_b32_e32 v86, v129
	v_mov_b32_e32 v87, v129
	v_mov_b32_e32 v92, 0
	v_mov_b32_e32 v93, 0
	v_mfma_f32_16x16x32_bf16 v[84:87], v[84:87], v[126:129], 0
	v_mfma_f32_16x16x32_bf16 v[64:67], v[88:91], v[64:67], v[84:87]
	s_nop 6
	v_cvt_pk_bf16_f32 v84, v16, v17
	v_cvt_pk_bf16_f32 v85, v18, v19
	v_cvt_pk_bf16_f32 v86, v0, v1
	v_cvt_pk_bf16_f32 v87, v2, v3
	s_nop 1
	v_mfma_f32_16x16x32_bf16 v[80:83], v[84:87], v[80:83], v[64:67]
	s_nop 2
	v_mov_b32_e32 v64, 0
	s_and_saveexec_b64 s[52:53], s[48:49]
	ds_read_b128 v[92:95], v182 offset:4608
	s_or_b64 exec, exec, s[52:53]
	v_mov_b32_e32 v65, 0
	v_mov_b32_e32 v66, 0
	v_mov_b32_e32 v67, 0
	s_and_saveexec_b64 s[52:53], s[48:49]
	ds_read_b128 v[64:67], v182 offset:6656
	s_or_b64 exec, exec, s[52:53]
	v_add_u32_e32 v181, v133, v138
	ds_read_b128 v[112:115], v181 offset:8704
	v_mov_b32_e32 v84, 0
	v_mov_b32_e32 v96, 0
	v_mov_b32_e32 v97, 0
	v_mov_b32_e32 v98, 0
	v_mov_b32_e32 v99, 0
	s_and_saveexec_b64 s[52:53], s[48:49]
	ds_read_b128 v[96:99], v182 offset:5120
	s_or_b64 exec, exec, s[52:53]
	v_mov_b32_e32 v85, 0
	v_mov_b32_e32 v86, 0
	v_mov_b32_e32 v87, 0
	s_and_saveexec_b64 s[52:53], s[48:49]
	ds_read_b128 v[84:87], v182 offset:7168
	s_or_b64 exec, exec, s[52:53]
	ds_read_b128 v[116:119], v181 offset:8768
	v_mov_b32_e32 v88, 0
	v_mov_b32_e32 v100, 0
	v_mov_b32_e32 v101, 0
	v_mov_b32_e32 v102, 0
	v_mov_b32_e32 v103, 0
	s_and_saveexec_b64 s[52:53], s[48:49]
	ds_read_b128 v[100:103], v182 offset:5632
	s_or_b64 exec, exec, s[52:53]
	v_mov_b32_e32 v89, 0
	v_mov_b32_e32 v90, 0
	v_mov_b32_e32 v91, 0
	s_and_saveexec_b64 s[52:53], s[48:49]
	ds_read_b128 v[88:91], v182 offset:7680
	s_or_b64 exec, exec, s[52:53]
	ds_read_b128 v[120:123], v181 offset:8832
	v_mov_b32_e32 v104, 0
	v_mov_b32_e32 v108, 0
	v_mov_b32_e32 v109, 0
	v_mov_b32_e32 v110, 0
	v_mov_b32_e32 v111, 0
	s_and_saveexec_b64 s[52:53], s[48:49]
	ds_read_b128 v[108:111], v182 offset:6144
	s_or_b64 exec, exec, s[52:53]
	v_mov_b32_e32 v105, 0
	v_mov_b32_e32 v106, 0
	v_mov_b32_e32 v107, 0
	s_and_saveexec_b64 s[52:53], s[48:49]
	ds_read_b128 v[104:107], v182 offset:8192
	s_or_b64 exec, exec, s[52:53]
	s_waitcnt lgkmcnt(2)
; __device__ __forceinline__ void hm_mfma(const LAS unsigned char* wl, f32x4 (&S)[4][4], f32x4 (&o)[4], int c16, int g) {
;     ...
; #pragma unroll
;     for (int mb = 0; mb < 4; ++mb)
; #pragma unroll
;         for (int nb = 0; nb < 4; ++nb) S[mb][nb] = __builtin_amdgcn_mfma_f32_16x16x32_bf16(af[mb], bf[nb], S[mb][nb] * e4[mb], 0, 0, 0);
	v_mul_f32_e32 v62, v62, v114
	v_mul_f32_e32 v63, v63, v115
	v_mul_f32_e32 v60, v60, v112
	v_mul_f32_e32 v61, v61, v113
	v_mul_f32_e32 v58, v58, v114
	v_mul_f32_e32 v59, v59, v115
	v_mul_f32_e32 v56, v56, v112
	v_mul_f32_e32 v57, v57, v113
	v_mul_f32_e32 v54, v54, v114
	v_mul_f32_e32 v55, v55, v115
	v_mul_f32_e32 v52, v52, v112
	v_mul_f32_e32 v53, v53, v113
	v_mul_f32_e32 v50, v50, v114
	v_mul_f32_e32 v51, v51, v115
	v_mul_f32_e32 v48, v48, v112
	v_mul_f32_e32 v49, v49, v113
	v_mfma_f32_16x16x32_bf16 v[60:63], v[92:95], v[64:67], v[60:63]
	s_waitcnt lgkmcnt(1)
	v_mul_f32_e32 v46, v46, v118
	v_mul_f32_e32 v47, v47, v119
	v_mul_f32_e32 v44, v44, v116
	v_mul_f32_e32 v45, v45, v117
	v_mul_f32_e32 v42, v42, v118
	v_mul_f32_e32 v43, v43, v119
	v_mfma_f32_16x16x32_bf16 v[56:59], v[92:95], v[84:87], v[56:59]
	v_mul_f32_e64 v40, v40, v116
	v_mul_f32_e64 v41, v41, v117
	s_waitcnt lgkmcnt(0)
	v_mul_f32_e32 v30, v30, v122
	v_mul_f32_e32 v31, v31, v123
	v_mul_f32_e32 v28, v28, v120
	v_mul_f32_e32 v29, v29, v121
	v_mfma_f32_16x16x32_bf16 v[52:55], v[92:95], v[88:91], v[52:55]
	v_mul_f32_e64 v26, v26, v122
	v_mul_f32_e64 v27, v27, v123
	v_mul_f32_e32 v24, v24, v120
	v_mul_f32_e32 v25, v25, v121
	v_mul_f32_e32 v38, v38, v118
	v_mul_f32_e32 v39, v39, v119
	v_mfma_f32_16x16x32_bf16 v[48:51], v[92:95], v[104:107], v[48:51]
	ds_read_b128 v[92:95], v181 offset:8896
	v_mul_f32_e32 v36, v36, v116
	v_mul_f32_e32 v37, v37, v117
	v_mul_f32_e32 v34, v34, v118
	v_mul_f32_e32 v35, v35, v119
	v_mfma_f32_16x16x32_bf16 v[44:47], v[96:99], v[64:67], v[44:47]
	v_mul_f32_e64 v32, v32, v116
	v_mul_f32_e64 v33, v33, v117
	s_waitcnt lgkmcnt(0)
	v_mul_f32_e32 v14, v14, v94
	v_mul_f32_e32 v15, v15, v95
	v_mul_f32_e32 v12, v12, v92
	v_mul_f32_e32 v13, v13, v93
	v_mul_f32_e32 v10, v10, v94
	v_mul_f32_e32 v11, v11, v95
	v_mul_f32_e32 v8, v8, v92
	v_mul_f32_e32 v9, v9, v93
	v_mfma_f32_16x16x32_bf16 v[40:43], v[96:99], v[84:87], v[40:43]
	v_mul_f32_e64 v22, v22, v122
	v_mul_f32_e64 v23, v23, v123
	v_mul_f32_e32 v20, v20, v120
	v_mul_f32_e32 v21, v21, v121
	v_mul_f32_e32 v18, v18, v122
	v_mul_f32_e32 v19, v19, v123
	v_mfma_f32_16x16x32_bf16 v[28:31], v[100:103], v[64:67], v[28:31]
	v_mul_f32_e64 v16, v16, v120
	v_mul_f32_e64 v17, v17, v121
	s_lshl_b32 s15, s9, 4
	v_add_u32_e32 v185, s8, v142
	v_mfma_f32_16x16x32_bf16 v[24:27], v[100:103], v[84:87], v[24:27]
	v_or_b32_e32 v184, s15, v142
	v_mfma_f32_16x16x32_bf16 v[12:15], v[108:111], v[64:67], v[12:15]
	v_mul_f32_e64 v66, v6, v94
	v_mul_f32_e64 v67, v7, v95
	v_mul_f32_e32 v64, v4, v92
	v_mul_f32_e32 v65, v5, v93
	v_subrev_u32_e32 v4, 63, v185
	v_mfma_f32_16x16x32_bf16 v[6:9], v[108:111], v[84:87], v[8:11]
	v_mul_f32_e64 v86, v2, v94
	v_mul_f32_e64 v87, v3, v95
	v_mul_f32_e32 v84, v0, v92
	v_mul_f32_e32 v85, v1, v93
	v_mfma_f32_16x16x32_bf16 v[36:39], v[96:99], v[88:91], v[36:39]
	v_mfma_f32_16x16x32_bf16 v[32:35], v[96:99], v[104:107], v[32:35]
	v_mfma_f32_16x16x32_bf16 v[20:23], v[100:103], v[88:91], v[20:23]
	v_mfma_f32_16x16x32_bf16 v[16:19], v[100:103], v[104:107], v[16:19]
	v_mfma_f32_16x16x32_bf16 v[0:3], v[108:111], v[88:91], v[64:67]
	v_mfma_f32_16x16x32_bf16 v[64:67], v[108:111], v[104:107], v[84:87]
	s_and_saveexec_b64 s[52:53], s[38:39]
	s_cbranch_execz .LBB0_584
	s_cmp_gt_u32 s9, 15
	s_mov_b64 vcc, -1
	s_cbranch_scc0 .LBB0_582
	v_sub_u32_e32 v4, 0x9ff, v184
	s_mov_b64 vcc, 0

; #define LAS __attribute__((address_space(3)))
; __device__ __forceinline__ unsigned pk2(float lo, float hi) { f32x2_t v = {lo, hi}; bf16x2_t b = __builtin_convertvector(v, bf16x2_t); return __builtin_bit_cast(unsigned, b); }
; __device__ __forceinline__ float fast_exp2(float x) { return __builtin_amdgcn_exp2f(x); }
; __device__ __forceinline__ void hm_stage(LAS unsigned char* wl, const unsigned (&rq)[16], const unsigned (&rz)[16], const unsigned (&rv)[16], float oml, int lane) {
;     ...
;     for (int i = 0; i < 16; ++i) {
;         const float z = bf2f(rz[i]), q = bf2f(rq[i]);
;         const float sg = __builtin_amdgcn_rcpf(1.0f + fast_exp2(z * LOG2E));
;         const float k = oml * sg;
;         run = fmaxf(run * (1.0f - k), 8.673617379884035e-19f);
;         const float ieb = __builtin_amdgcn_rcpf(run);
;         kt[i] = k * ieb;
;         *(LAS unsigned short*)(wl + HM_QT + i * HM_QP + lane * 2) = (unsigned short)pk2(q * run, 0.f);
;         *(LAS unsigned short*)(wl + HM_KT + i * HM_QP + lane * 2) = (unsigned short)pk2(kt[i], 0.f);
;         if (i & 1) vpk[i >> 1] = rv[i - 1] | (rv[i] << 16);
;     }
.LBB0_584:
	s_or_b64 exec, exec, s[52:53]
	v_ashrrev_i32_e32 v5, 31, v4
	v_lshl_add_u64 v[4:5], v[4:5], 0, s[64:65]
	v_lshlrev_b64 v[4:5], 10, v[4:5]
	v_lshl_add_u64 v[4:5], v[140:141], 0, v[4:5]
	global_store_dwordx4 v[4:5], v[68:71], off
	global_store_dwordx4 v[4:5], v[72:75], off offset:64
	global_store_dwordx4 v[4:5], v[76:79], off offset:128
	global_store_dwordx4 v[4:5], v[80:83], off offset:192
	s_waitcnt vmcnt(52)
	v_lshlrev_b32_e32 v4, 16, v216
	v_mul_f32_e32 v4, 0x3fb8aa3b, v4
	v_exp_f32_e32 v4, v4
	v_lshlrev_b32_e32 v89, 16, v214
	v_lshlrev_b32_e32 v90, 16, v213
	v_lshlrev_b32_e32 v91, 16, v212
	v_add_f32_e32 v4, 1.0, v4
	v_rcp_f32_e32 v10, v4
	v_lshlrev_b32_e32 v4, 16, v215
	v_mul_f32_e32 v4, 0x3fb8aa3b, v4
	v_exp_f32_e32 v4, v4
	v_lshlrev_b32_e32 v92, 16, v220
	v_lshlrev_b32_e32 v93, 16, v219
	v_lshlrev_b32_e32 v94, 16, v229
	v_add_f32_e32 v4, 1.0, v4
	v_rcp_f32_e32 v11, v4
	v_lshlrev_b32_e32 v4, 16, v224
	v_mul_f32_e32 v4, 0x3fb8aa3b, v4
	v_exp_f32_e32 v4, v4
	v_mul_f32_e32 v10, v136, v10
	v_mul_f32_e32 v11, v137, v11
	v_lshlrev_b32_e32 v95, 16, v228
	v_sub_f32_e32 v88, 1.0, v10
	v_max_f32_e32 v119, 0x21800000, v88
	v_add_f32_e32 v4, 1.0, v4
	v_mul_f32_e32 v89, v119, v89
	v_rcp_f32_e32 v78, v4
	v_lshlrev_b32_e32 v4, 16, v222
	v_cvt_pk_bf16_f32 v89, v89, s0
	v_mul_f32_e32 v4, 0x3fb8aa3b, v4
	ds_write_b16 v139, v89
	v_sub_f32_e32 v89, 1.0, v11
	v_exp_f32_e32 v4, v4
	v_mul_f32_e32 v89, v89, v119
	v_rcp_f32_e32 v88, v119
	v_max_f32_e32 v119, 0x21800000, v89
	v_rcp_f32_e32 v89, v119
	v_add_f32_e32 v4, 1.0, v4
	v_rcp_f32_e32 v79, v4
	v_lshlrev_b32_e32 v4, 16, v221
	v_mul_f32_e32 v4, 0x3fb8aa3b, v4
	v_mul_f32_e32 v10, v10, v88
	v_mul_f32_e32 v11, v11, v89
	v_exp_f32_e32 v4, v4
	v_cvt_pk_bf16_f32 v88, v10, s0
	ds_write_b16 v139, v88 offset:2304
	v_mul_f32_e32 v88, v119, v90
	v_mul_f32_e32 v78, v136, v78
	v_mul_f32_e32 v79, v137, v79
	v_cvt_pk_bf16_f32 v88, v88, s0
	v_sub_f32_e32 v117, 1.0, v78
	ds_write_b16 v139, v88 offset:144
	v_cvt_pk_bf16_f32 v88, v11, s0
	v_add_f32_e32 v4, 1.0, v4
	ds_write_b16 v139, v88 offset:2448
	v_mul_f32_e32 v88, v117, v119
	v_rcp_f32_e32 v82, v4
	v_lshlrev_b32_e32 v4, 16, v231
	v_max_f32_e32 v89, 0x21800000, v88
	v_mul_f32_e32 v4, 0x3fb8aa3b, v4
	v_sub_f32_e32 v118, 1.0, v79
	v_mul_f32_e32 v90, v89, v91
	v_exp_f32_e32 v4, v4
	v_rcp_f32_e32 v88, v89
	v_cvt_pk_bf16_f32 v90, v90, s0
	v_mul_f32_e32 v89, v118, v89
	ds_write_b16 v139, v90 offset:288
	v_max_f32_e32 v90, 0x21800000, v89
	v_rcp_f32_e32 v89, v90
	v_add_f32_e32 v4, 1.0, v4
	v_rcp_f32_e32 v83, v4
	v_lshlrev_b32_e32 v4, 16, v230
	v_mul_f32_e32 v4, 0x3fb8aa3b, v4
	v_mul_f32_e32 v78, v78, v88
	v_mul_f32_e32 v79, v79, v89
	v_exp_f32_e32 v4, v4
	v_cvt_pk_bf16_f32 v88, v78, s0
	ds_write_b16 v139, v88 offset:2592
	v_mul_f32_e32 v88, v90, v92
	v_mul_f32_e32 v82, v136, v82
	v_mul_f32_e32 v83, v137, v83
	v_cvt_pk_bf16_f32 v88, v88, s0
	v_sub_f32_e32 v115, 1.0, v82
	ds_write_b16 v139, v88 offset:432
	v_cvt_pk_bf16_f32 v88, v79, s0
	v_add_f32_e32 v4, 1.0, v4
	ds_write_b16 v139, v88 offset:2736
	v_mul_f32_e32 v88, v115, v90
	v_rcp_f32_e32 v84, v4
	v_lshlrev_b32_e32 v4, 16, v240
	v_max_f32_e32 v89, 0x21800000, v88
	v_mul_f32_e32 v4, 0x3fb8aa3b, v4
	v_sub_f32_e32 v116, 1.0, v83
	v_mul_f32_e32 v90, v89, v93
	v_exp_f32_e32 v4, v4
	v_rcp_f32_e32 v88, v89
	v_cvt_pk_bf16_f32 v90, v90, s0
	v_mul_f32_e32 v89, v116, v89
	ds_write_b16 v139, v90 offset:576
	v_max_f32_e32 v90, 0x21800000, v89
	v_rcp_f32_e32 v89, v90
	v_add_f32_e32 v4, 1.0, v4
	v_rcp_f32_e32 v85, v4
	v_lshlrev_b32_e32 v4, 16, v239
	v_mul_f32_e32 v4, 0x3fb8aa3b, v4
	v_mul_f32_e32 v82, v82, v88
	v_mul_f32_e32 v83, v83, v89
	v_exp_f32_e32 v4, v4
	v_cvt_pk_bf16_f32 v88, v82, s0
	ds_write_b16 v139, v88 offset:2880
	v_mul_f32_e32 v88, v90, v94
	v_mul_f32_e32 v84, v136, v84
	v_mul_f32_e32 v85, v137, v85
	v_cvt_pk_bf16_f32 v88, v88, s0
	v_sub_f32_e32 v113, 1.0, v84
	ds_write_b16 v139, v88 offset:720
	v_cvt_pk_bf16_f32 v88, v83, s0
	v_add_f32_e32 v4, 1.0, v4
	ds_write_b16 v139, v88 offset:3024
	v_mul_f32_e32 v88, v113, v90
	v_rcp_f32_e32 v86, v4
	v_lshlrev_b32_e32 v4, 16, v238
	v_max_f32_e32 v89, 0x21800000, v88
	v_mul_f32_e32 v4, 0x3fb8aa3b, v4
	v_sub_f32_e32 v114, 1.0, v85
	v_mul_f32_e32 v90, v89, v95
	v_exp_f32_e32 v4, v4
	v_rcp_f32_e32 v88, v89
	v_cvt_pk_bf16_f32 v90, v90, s0
	v_mul_f32_e32 v89, v114, v89
	ds_write_b16 v139, v90 offset:864
	v_max_f32_e32 v90, 0x21800000, v89
	v_rcp_f32_e32 v89, v90
	v_add_f32_e32 v4, 1.0, v4
	v_rcp_f32_e32 v87, v4
	v_lshlrev_b32_e32 v4, 16, v248
	v_mul_f32_e32 v4, 0x3fb8aa3b, v4
	v_mul_f32_e32 v84, v84, v88
	v_mul_f32_e32 v85, v85, v89
	v_lshlrev_b32_e32 v96, 16, v227
	v_exp_f32_e32 v4, v4
	v_cvt_pk_bf16_f32 v88, v84, s0
	ds_write_b16 v139, v88 offset:3168
	v_mul_f32_e32 v88, v90, v96
	v_mul_f32_e32 v86, v136, v86
	v_mul_f32_e32 v87, v137, v87
	v_cvt_pk_bf16_f32 v88, v88, s0
	v_sub_f32_e32 v111, 1.0, v86
	ds_write_b16 v139, v88 offset:1008
	v_cvt_pk_bf16_f32 v88, v85, s0
	v_add_f32_e32 v4, 1.0, v4
	ds_write_b16 v139, v88 offset:3312
	v_mul_f32_e32 v88, v111, v90
	v_lshlrev_b32_e32 v97, 16, v237
	v_rcp_f32_e32 v80, v4
; #define LAS __attribute__((address_space(3)))
; __device__ __forceinline__ unsigned pk2(float lo, float hi) { f32x2_t v = {lo, hi}; bf16x2_t b = __builtin_convertvector(v, bf16x2_t); return __builtin_bit_cast(unsigned, b); }
; #define HM_LOAD(RQ, RZ, RV, j_) do { _Pragma("unroll") for (int i = 0; i < 16; ++i) { const bf16_t* pr_ = proj + HM_TOK((j_) * 16 + i) * INW; RQ[i] = pr_[qc]; RZ[i] = pr_[zc]; RV[i] = pr_[vc]; } } while (0)
; __device__ __forceinline__ void hm_stage(LAS unsigned char* wl, const unsigned (&rq)[16], const unsigned (&rz)[16], const unsigned (&rv)[16], float oml, int lane) {
;     ...
;         run = fmaxf(run * (1.0f - k), 8.673617379884035e-19f);
;         const float ieb = __builtin_amdgcn_rcpf(run);
;         kt[i] = k * ieb;
;         *(LAS unsigned short*)(wl + HM_QT + i * HM_QP + lane * 2) = (unsigned short)pk2(q * run, 0.f);
;         *(LAS unsigned short*)(wl + HM_KT + i * HM_QP + lane * 2) = (unsigned short)pk2(kt[i], 0.f);
;         if (i & 1) vpk[i >> 1] = rv[i - 1] | (rv[i] << 16);
;     }
;     const float eB = run;
;     *(LAS float*)(wl + HM_EB + lane * 4) = eB;
;     u32x4 w0, w1;
;     w0.x = pk2(kt[0] * eB, kt[1] * eB); w0.y = pk2(kt[2] * eB, kt[3] * eB); w0.z = pk2(kt[4] * eB, kt[5] * eB); w0.w = pk2(kt[6] * eB, kt[7] * eB);
;     w1.x = pk2(kt[8] * eB, kt[9] * eB); w1.y = pk2(kt[10] * eB, kt[11] * eB); w1.z = pk2(kt[12] * eB, kt[13] * eB); w1.w = pk2(kt[14] * eB, kt[15] * eB);
;     *(LAS u32x4*)(wl + HM_KD + lane * 32) = w0; *(LAS u32x4*)(wl + HM_KD + lane * 32 + 16) = w1;
;     *(LAS u32x4*)(wl + HM_VT + lane * 32) = (u32x4){vpk[0], vpk[1], vpk[2], vpk[3]}; *(LAS u32x4*)(wl + HM_VT + lane * 32 + 16) = (u32x4){vpk[4], vpk[5], vpk[6], vpk[7]};
; __device__ __forceinline__ void hgrn_mfma_unit(const Params& P, int l, LAS unsigned char* lds, int b, int half) {
;     ...
;             if (j + 3 < NSC) HM_LOAD(bq, bz, bv, j + 3);
	v_lshlrev_b32_e32 v4, 16, v246
	v_max_f32_e32 v89, 0x21800000, v88
	v_mul_f32_e32 v4, 0x3fb8aa3b, v4
	v_sub_f32_e32 v112, 1.0, v87
	v_mul_f32_e32 v90, v89, v97
	v_exp_f32_e32 v4, v4
	v_rcp_f32_e32 v88, v89
	v_cvt_pk_bf16_f32 v90, v90, s0
	v_mul_f32_e32 v89, v112, v89
	ds_write_b16 v139, v90 offset:1152
	v_max_f32_e32 v90, 0x21800000, v89
	v_rcp_f32_e32 v89, v90
	v_add_f32_e32 v4, 1.0, v4
	v_rcp_f32_e32 v81, v4
	v_lshlrev_b32_e32 v4, 16, v245
	v_mul_f32_e32 v4, 0x3fb8aa3b, v4
	v_mul_f32_e32 v86, v86, v88
	v_mul_f32_e32 v87, v87, v89
	v_lshlrev_b32_e32 v98, 16, v236
	v_exp_f32_e32 v4, v4
	v_cvt_pk_bf16_f32 v88, v86, s0
	ds_write_b16 v139, v88 offset:3456
	v_mul_f32_e32 v88, v90, v98
	v_mul_f32_e32 v80, v136, v80
	v_mul_f32_e32 v81, v137, v81
	v_cvt_pk_bf16_f32 v88, v88, s0
	v_sub_f32_e32 v109, 1.0, v80
	ds_write_b16 v139, v88 offset:1296
	v_cvt_pk_bf16_f32 v88, v87, s0
	v_add_f32_e32 v4, 1.0, v4
	ds_write_b16 v139, v88 offset:3600
	v_mul_f32_e32 v88, v109, v90
	v_lshlrev_b32_e32 v99, 16, v235
	v_rcp_f32_e32 v76, v4
	v_lshlrev_b32_e32 v4, 16, v206
	v_max_f32_e32 v89, 0x21800000, v88
	v_mul_f32_e32 v4, 0x3fb8aa3b, v4
	v_sub_f32_e32 v110, 1.0, v81
	v_mul_f32_e32 v90, v89, v99
	v_exp_f32_e32 v4, v4
	v_rcp_f32_e32 v88, v89
	v_cvt_pk_bf16_f32 v90, v90, s0
	v_mul_f32_e32 v89, v110, v89
	ds_write_b16 v139, v90 offset:1440
	v_max_f32_e32 v90, 0x21800000, v89
	v_rcp_f32_e32 v89, v90
	v_add_f32_e32 v4, 1.0, v4
	v_rcp_f32_e32 v77, v4
	v_lshlrev_b32_e32 v100, 16, v244
	v_mul_f32_e32 v88, v80, v88
	v_mul_f32_e32 v89, v81, v89
	v_lshlrev_b32_e32 v4, 16, v204
	v_cvt_pk_bf16_f32 v80, v88, s0
	ds_write_b16 v139, v80 offset:3744
	v_mul_f32_e32 v80, v90, v100
	v_mul_f32_e32 v76, v136, v76
	v_mul_f32_e32 v77, v137, v77
	v_cvt_pk_bf16_f32 v80, v80, s0
	v_sub_f32_e32 v107, 1.0, v76
	ds_write_b16 v139, v80 offset:1584
	v_cvt_pk_bf16_f32 v80, v89, s0
	v_lshlrev_b32_e32 v5, 16, v178
	ds_write_b16 v139, v80 offset:3888
	v_mul_f32_e32 v80, v107, v90
	v_lshlrev_b32_e32 v101, 16, v243
	v_mul_f32_e32 v4, 0x3fb8aa3b, v4
	v_mul_f32_e32 v5, 0x3fb8aa3b, v5
	v_sub_f32_e32 v108, 1.0, v77
	v_max_f32_e32 v81, 0x21800000, v80
	v_exp_f32_e32 v4, v4
	v_exp_f32_e32 v5, v5
	v_rcp_f32_e32 v80, v81
	v_mul_f32_e32 v90, v81, v101
	v_mul_f32_e32 v81, v108, v81
	v_max_f32_e32 v92, 0x21800000, v81
	v_rcp_f32_e32 v81, v92
	v_add_f32_e32 v4, 1.0, v4
	v_add_f32_e32 v5, 1.0, v5
	v_rcp_f32_e32 v4, v4
	v_rcp_f32_e32 v5, v5
	v_cvt_pk_bf16_f32 v90, v90, s0
	ds_write_b16 v139, v90 offset:1728
	v_mul_f32_e32 v90, v76, v80
	v_mul_f32_e32 v91, v77, v81
	v_lshlrev_b32_e32 v102, 16, v205
	v_cvt_pk_bf16_f32 v76, v90, s0
	ds_write_b16 v139, v76 offset:4032
	v_mul_f32_e32 v76, v92, v102
	v_mul_f32_e32 v4, v136, v4
	v_mul_f32_e32 v5, v137, v5
	v_cvt_pk_bf16_f32 v76, v76, s0
	v_sub_f32_e32 v105, 1.0, v4
	ds_write_b16 v139, v76 offset:1872
	v_cvt_pk_bf16_f32 v76, v91, s0
	ds_write_b16 v139, v76 offset:4176
	v_mul_f32_e32 v76, v105, v92
	v_lshlrev_b32_e32 v103, 16, v252
	v_sub_f32_e32 v106, 1.0, v5
	v_max_f32_e32 v77, 0x21800000, v76
	v_rcp_f32_e32 v76, v77
	v_mul_f32_e32 v80, v77, v103
	v_mul_f32_e32 v77, v106, v77
	v_max_f32_e32 v92, 0x21800000, v77
	v_rcp_f32_e32 v77, v92
	v_lshlrev_b32_e32 v104, 16, v251
	v_cvt_pk_bf16_f32 v80, v80, s0
	v_mul_f32_e32 v10, v10, v92
	v_mul_f32_e32 v11, v11, v92
	v_mul_f32_e32 v4, v4, v76
	v_mul_f32_e32 v5, v5, v77
	ds_write_b16 v139, v80 offset:2016
	v_cvt_pk_bf16_f32 v76, v4, s0
	ds_write_b16 v139, v76 offset:4320
	v_mul_f32_e32 v76, v92, v104
	v_cvt_pk_bf16_f32 v76, v76, s0
	ds_write_b16 v139, v76 offset:2160
	v_cvt_pk_bf16_f32 v76, v5, s0
	ds_write_b16 v139, v76 offset:4464
	ds_write_b32 v207, v92 offset:8704
	v_cvt_pk_bf16_f32 v76, v10, v11
	v_mul_f32_e32 v10, v78, v92
	v_mul_f32_e32 v11, v79, v92
	v_mul_f32_e32 v4, v4, v92
	v_mul_f32_e32 v5, v5, v92
	v_cvt_pk_bf16_f32 v77, v10, v11
	v_mul_f32_e32 v10, v82, v92
	v_mul_f32_e32 v11, v83, v92
	s_cmpk_gt_u32 s9, 0x8c
	v_cvt_pk_bf16_f32 v78, v10, v11
	v_mul_f32_e32 v10, v84, v92
	v_mul_f32_e32 v11, v85, v92
	v_lshl_or_b32 v68, v217, 16, v218
	v_cvt_pk_bf16_f32 v79, v10, v11
	v_mul_f32_e32 v10, v86, v92
	v_mul_f32_e32 v11, v87, v92
	v_lshl_or_b32 v69, v225, 16, v226
	v_cvt_pk_bf16_f32 v80, v10, v11
	v_mul_f32_e32 v10, v88, v92
	v_mul_f32_e32 v11, v89, v92
	v_lshl_or_b32 v70, v234, 16, v223
	v_cvt_pk_bf16_f32 v81, v10, v11
	v_mul_f32_e32 v10, v90, v92
	v_mul_f32_e32 v11, v91, v92
	v_lshl_or_b32 v71, v232, 16, v233
	v_lshl_or_b32 v72, v241, 16, v242
	v_lshl_or_b32 v73, v249, 16, v250
	v_lshl_or_b32 v74, v180, 16, v247
	v_lshl_or_b32 v75, v208, 16, v179
	v_cvt_pk_bf16_f32 v82, v10, v11
	v_cvt_pk_bf16_f32 v83, v4, v5
	ds_write_b128 v146, v[76:79] offset:4608
	ds_write_b128 v146, v[80:83] offset:4624
	ds_write_b128 v146, v[68:71] offset:6656
	ds_write_b128 v146, v[72:75] offset:6672
	s_cbranch_scc1 .LBB0_697
	s_add_u32 s12, s15, 48
	s_mov_b32 s18, 0x1600
	s_mov_b32 s19, 0
	s_cmp_eq_u64 s[38:39], 0
	s_cbranch_scc1 .Lhm_b_go
	s_cmp_lt_u32 s9, 13
	s_movk_i32 s13, 0x9ff
	s_cselect_b32 s13, 0xff, s13
	s_sub_u32 s12, s13, s12
	s_mov_b32 s18, 0xffffea00
	s_mov_b32 s19, -1

; #define LAS __attribute__((address_space(3)))
; __device__ __forceinline__ void hm_mfma(const LAS unsigned char* wl, f32x4 (&S)[4][4], f32x4 (&o)[4], int c16, int g) {
;     const bf16x8 zero8 = {0, 0, 0, 0, 0, 0, 0, 0};
;     f32x4 sc = (f32x4){0.f, 0.f, 0.f, 0.f};
; #pragma unroll
;     for (int kk = 0; kk < 2; ++kk) {
;         const bf16x8 a = *(const LAS bf16x8*)(wl + HM_KT + c16 * HM_QP + (32 * kk + 8 * g) * 2);
;         const bf16x8 bq = *(const LAS bf16x8*)(wl + HM_QT + c16 * HM_QP + (32 * kk + 8 * g) * 2);
;         sc = __builtin_amdgcn_mfma_f32_16x16x32_bf16(a, bq, sc, 0, 0, 0);
;     }
; #pragma unroll
;     for (int r = 0; r < 4; ++r) if (4 * g + r > c16) sc[r] = 0.f;
;     bf16x8 pb; { u32x4 w; w.x = pk2(sc[0], sc[1]); w.y = pk2(sc[2], sc[3]); w.z = 0u; w.w = 0u; pb = __builtin_bit_cast(bf16x8, w); }
;     bf16x8 qb[2];
; #pragma unroll
;     for (int kk = 0; kk < 2; ++kk) {
;         const u32x2 lo = *(const LAS u32x2*)(wl + HM_QT + c16 * HM_QP + (32 * kk + 4 * g) * 2), hi2 = *(const LAS u32x2*)(wl + HM_QT + c16 * HM_QP + (32 * kk + 16 + 4 * g) * 2);
;         qb[kk] = __builtin_bit_cast(bf16x8, ((u32x4){lo.x, lo.y, hi2.x, hi2.y}));
;     }
; #pragma unroll
;     for (int eb = 0; eb < 4; ++eb) {
;         const u32x2 va = *(const LAS u32x2*)(wl + HM_VT + (16 * eb + c16) * 32 + 8 * g);
;         const bf16x8 a = __builtin_bit_cast(bf16x8, ((u32x4){va.x, va.y, 0u, 0u}));
;         f32x4 acc = __builtin_amdgcn_mfma_f32_16x16x32_bf16(a, pb, (f32x4){0.f, 0.f, 0.f, 0.f}, 0, 0, 0);
; #pragma unroll
;         for (int kk = 0; kk < 2; ++kk) {
;             const f32x4 s0 = S[2 * kk][eb], s1 = S[2 * kk + 1][eb];
;             u32x4 w; w.x = pk2(s0[0], s0[1]); w.y = pk2(s0[2], s0[3]); w.z = pk2(s1[0], s1[1]); w.w = pk2(s1[2], s1[3]);
;             acc = __builtin_amdgcn_mfma_f32_16x16x32_bf16(__builtin_bit_cast(bf16x8, w), qb[kk], acc, 0, 0, 0);
;         }
;         o[eb] = acc;
;     }
;     bf16x8 af[4], bf[4]; f32x4 e4[4];
; #pragma unroll
;     for (int x = 0; x < 4; ++x) {
;         af[x] = (g < 2) ? *(const LAS bf16x8*)(wl + HM_KD + (16 * x + c16) * 32 + 16 * g) : zero8;
;         bf[x] = (g < 2) ? *(const LAS bf16x8*)(wl + HM_VT + (16 * x + c16) * 32 + 16 * g) : zero8;
;         e4[x] = *(const LAS f32x4*)(wl + HM_EB + (16 * x + 4 * g) * 4);
;     }
.LBB0_697:
	ds_read_b128 v[68:71], v183 offset:2304
	ds_read_b128 v[72:75], v183 offset:2368
	ds_read_b128 v[76:79], v183
	ds_read_b128 v[80:83], v183 offset:64
	ds_read2st64_b64 v[84:87], v124 offset0:13 offset1:14
	ds_read2st64_b64 v[92:95], v124 offset0:15 offset1:16
	v_mov_b32_e32 v90, v129
	s_waitcnt lgkmcnt(3)
	v_mfma_f32_16x16x32_bf16 v[68:71], v[68:71], v[76:79], 0
	v_mov_b32_e32 v91, v129
	s_waitcnt lgkmcnt(1)
	v_mov_b32_e32 v88, v84
	v_mov_b32_e32 v89, v85
	v_mfma_f32_16x16x32_bf16 v[68:71], v[72:75], v[80:83], v[68:71]
	v_mov_b32_e32 v4, s65
	ds_read2_b64 v[80:83], v125 offset1:4
	v_mov_b32_e32 v128, v129
	v_cvt_pk_bf16_f32 v72, v60, v61
	v_cvt_pk_bf16_f32 v73, v62, v63
	s_nop 2
	v_cndmask_b32_e64 v4, v68, v4, s[40:41]
	v_cndmask_b32_e64 v5, 0, v69, s[42:43]
	v_cndmask_b32_e64 v10, v70, 0, s[44:45]
	v_cndmask_b32_e64 v11, v71, 0, s[46:47]
	v_cndmask_b32_e64 v4, v4, v68, s[42:43]
	v_cvt_pk_bf16_f32 v127, v10, v11
	v_cvt_pk_bf16_f32 v126, v4, v5
	v_cvt_pk_bf16_f32 v74, v44, v45
	v_cvt_pk_bf16_f32 v75, v46, v47
	v_mfma_f32_16x16x32_bf16 v[68:71], v[88:91], v[126:129], 0
	ds_read2_b64 v[88:91], v125 offset0:8 offset1:12
	v_cvt_pk_bf16_f32 v76, v56, v57
	v_cvt_pk_bf16_f32 v77, v58, v59
	s_waitcnt lgkmcnt(1)
	v_mfma_f32_16x16x32_bf16 v[68:71], v[72:75], v[80:83], v[68:71]
	v_cvt_pk_bf16_f32 v72, v28, v29
	v_cvt_pk_bf16_f32 v73, v30, v31
	v_cvt_pk_bf16_f32 v74, v12, v13
	v_cvt_pk_bf16_f32 v75, v14, v15
	v_cvt_pk_bf16_f32 v78, v40, v41
	v_cvt_pk_bf16_f32 v79, v42, v43
	s_waitcnt lgkmcnt(0)
	v_mfma_f32_16x16x32_bf16 v[68:71], v[72:75], v[88:91], v[68:71]
	v_mov_b32_e32 v72, v86
	v_mov_b32_e32 v73, v87
	v_mov_b32_e32 v74, v129
	v_mov_b32_e32 v75, v129
	v_cvt_pk_bf16_f32 v84, v52, v53
	v_cvt_pk_bf16_f32 v85, v54, v55
	v_mfma_f32_16x16x32_bf16 v[72:75], v[72:75], v[126:129], 0
	v_cvt_pk_bf16_f32 v86, v36, v37
	v_cvt_pk_bf16_f32 v87, v38, v39
	v_mov_b32_e32 v96, 0
	v_mfma_f32_16x16x32_bf16 v[72:75], v[76:79], v[80:83], v[72:75]
	v_cvt_pk_bf16_f32 v76, v24, v25
	v_cvt_pk_bf16_f32 v77, v26, v27
	v_cvt_pk_bf16_f32 v78, v6, v7
	v_cvt_pk_bf16_f32 v79, v8, v9
	v_mov_b32_e32 v97, 0
	v_mov_b32_e32 v98, 0
	v_mfma_f32_16x16x32_bf16 v[72:75], v[76:79], v[88:91], v[72:75]
	v_mov_b32_e32 v76, v92
	v_mov_b32_e32 v77, v93
	v_mov_b32_e32 v78, v129
	v_mov_b32_e32 v79, v129
	v_cvt_pk_bf16_f32 v92, v48, v49
	v_cvt_pk_bf16_f32 v93, v50, v51
	v_mfma_f32_16x16x32_bf16 v[76:79], v[76:79], v[126:129], 0
	v_mov_b32_e32 v99, 0
	v_mfma_f32_16x16x32_bf16 v[76:79], v[84:87], v[80:83], v[76:79]
	v_cvt_pk_bf16_f32 v84, v20, v21
	v_cvt_pk_bf16_f32 v85, v22, v23
	v_cvt_pk_bf16_f32 v86, v0, v1
	v_cvt_pk_bf16_f32 v87, v2, v3
	s_nop 1
	v_mfma_f32_16x16x32_bf16 v[76:79], v[84:87], v[88:91], v[76:79]
	v_mov_b32_e32 v84, v94
	v_mov_b32_e32 v85, v95
	v_mov_b32_e32 v86, v129
	v_mov_b32_e32 v87, v129
	v_cvt_pk_bf16_f32 v94, v32, v33
	v_cvt_pk_bf16_f32 v95, v34, v35
	v_mfma_f32_16x16x32_bf16 v[84:87], v[84:87], v[126:129], 0
	s_nop 0
	v_mfma_f32_16x16x32_bf16 v[80:83], v[92:95], v[80:83], v[84:87]
	s_nop 5
	v_cvt_pk_bf16_f32 v84, v16, v17
	v_cvt_pk_bf16_f32 v85, v18, v19
	v_cvt_pk_bf16_f32 v86, v64, v65
	v_cvt_pk_bf16_f32 v87, v66, v67
	s_nop 1
	v_mfma_f32_16x16x32_bf16 v[80:83], v[84:87], v[88:91], v[80:83]
	v_mov_b32_e32 v84, 0
	s_and_saveexec_b64 s[52:53], s[48:49]
	ds_read_b128 v[96:99], v182 offset:4608
	s_or_b64 exec, exec, s[52:53]
	v_mov_b32_e32 v85, 0
	v_mov_b32_e32 v86, 0
	v_mov_b32_e32 v87, 0
	s_and_saveexec_b64 s[52:53], s[48:49]
	ds_read_b128 v[84:87], v182 offset:6656
	s_or_b64 exec, exec, s[52:53]
	ds_read_b128 v[116:119], v181 offset:8704
	v_mov_b32_e32 v88, 0
	v_mov_b32_e32 v100, 0
	v_mov_b32_e32 v101, 0
	v_mov_b32_e32 v102, 0
	v_mov_b32_e32 v103, 0
	s_and_saveexec_b64 s[52:53], s[48:49]
	ds_read_b128 v[100:103], v182 offset:5120
	s_or_b64 exec, exec, s[52:53]
	v_mov_b32_e32 v89, 0
	v_mov_b32_e32 v90, 0
	v_mov_b32_e32 v91, 0
	s_and_saveexec_b64 s[52:53], s[48:49]
	ds_read_b128 v[88:91], v182 offset:7168
	s_or_b64 exec, exec, s[52:53]
	ds_read_b128 v[120:123], v181 offset:8768
	v_mov_b32_e32 v92, 0
	v_mov_b32_e32 v104, 0
	v_mov_b32_e32 v105, 0
	v_mov_b32_e32 v106, 0
	v_mov_b32_e32 v107, 0
	s_and_saveexec_b64 s[52:53], s[48:49]
	ds_read_b128 v[104:107], v182 offset:5632
	s_or_b64 exec, exec, s[52:53]
	v_mov_b32_e32 v93, 0
	v_mov_b32_e32 v94, 0
	v_mov_b32_e32 v95, 0
	s_and_saveexec_b64 s[52:53], s[48:49]
	ds_read_b128 v[92:95], v182 offset:7680
	s_or_b64 exec, exec, s[52:53]
	ds_read_b128 v[124:127], v181 offset:8832
	v_mov_b32_e32 v108, 0
	v_mov_b32_e32 v112, 0
	v_mov_b32_e32 v113, 0
	v_mov_b32_e32 v114, 0
	v_mov_b32_e32 v115, 0
	s_and_saveexec_b64 s[52:53], s[48:49]
	ds_read_b128 v[112:115], v182 offset:6144
	s_or_b64 exec, exec, s[52:53]
	v_mov_b32_e32 v109, 0
	v_mov_b32_e32 v110, 0
	v_mov_b32_e32 v111, 0
	s_and_saveexec_b64 s[52:53], s[48:49]
	ds_read_b128 v[108:111], v182 offset:8192
	s_or_b64 exec, exec, s[52:53]
	s_waitcnt lgkmcnt(2)
; __device__ __forceinline__ void hm_mfma(const LAS unsigned char* wl, f32x4 (&S)[4][4], f32x4 (&o)[4], int c16, int g) {
;     ...
; #pragma unroll
;     for (int mb = 0; mb < 4; ++mb)
; #pragma unroll
;         for (int nb = 0; nb < 4; ++nb) S[mb][nb] = __builtin_amdgcn_mfma_f32_16x16x32_bf16(af[mb], bf[nb], S[mb][nb] * e4[mb], 0, 0, 0);
	v_mul_f32_e32 v62, v62, v118
	v_mul_f32_e32 v63, v63, v119
	v_mul_f32_e32 v60, v60, v116
	v_mul_f32_e32 v61, v61, v117
	v_mul_f32_e32 v58, v58, v118
	v_mul_f32_e32 v59, v59, v119
	v_mul_f32_e32 v56, v56, v116
	v_mul_f32_e32 v57, v57, v117
	v_mul_f32_e32 v54, v54, v118
	v_mul_f32_e32 v55, v55, v119
	v_mul_f32_e32 v52, v52, v116
	v_mul_f32_e32 v53, v53, v117
	v_mul_f32_e32 v50, v50, v118
	v_mul_f32_e32 v51, v51, v119
	v_mul_f32_e32 v48, v48, v116
	v_mul_f32_e32 v49, v49, v117
	v_mfma_f32_16x16x32_bf16 v[60:63], v[96:99], v[84:87], v[60:63]
	s_waitcnt lgkmcnt(1)
	v_mul_f32_e32 v46, v46, v122
	v_mul_f32_e32 v47, v47, v123
	v_mul_f32_e32 v44, v44, v120
	v_mul_f32_e32 v45, v45, v121
	v_mul_f32_e32 v42, v42, v122
	v_mul_f32_e32 v43, v43, v123
	v_mfma_f32_16x16x32_bf16 v[56:59], v[96:99], v[88:91], v[56:59]
	v_mul_f32_e64 v40, v40, v120
	v_mul_f32_e64 v41, v41, v121
	v_mul_f32_e32 v38, v38, v122
	v_mul_f32_e32 v39, v39, v123
	v_mul_f32_e32 v36, v36, v120
	v_mul_f32_e32 v37, v37, v121
	v_mfma_f32_16x16x32_bf16 v[52:55], v[96:99], v[92:95], v[52:55]
	v_mul_f32_e64 v34, v34, v122
	v_mul_f32_e64 v35, v35, v123
	v_mul_f32_e32 v32, v32, v120
	v_mul_f32_e32 v33, v33, v121
	s_waitcnt lgkmcnt(0)
	v_mul_f32_e32 v30, v30, v126
	v_mul_f32_e32 v31, v31, v127
	v_mfma_f32_16x16x32_bf16 v[48:51], v[96:99], v[108:111], v[48:51]
	ds_read_b128 v[96:99], v181 offset:8896
	v_mul_f32_e32 v28, v28, v124
	v_mul_f32_e32 v29, v29, v125
	v_mul_f32_e32 v26, v26, v126
	v_mul_f32_e32 v27, v27, v127
	v_mul_f32_e32 v24, v24, v124
	v_mul_f32_e32 v25, v25, v125
	v_mul_f32_e32 v22, v22, v126
	v_mul_f32_e32 v23, v23, v127
	s_waitcnt lgkmcnt(0)
	v_mul_f32_e32 v8, v8, v98
	v_mul_f32_e32 v9, v9, v99
	v_mul_f32_e32 v6, v6, v96
	v_mul_f32_e32 v7, v7, v97
	v_mul_f32_e32 v2, v2, v98
	v_mul_f32_e32 v3, v3, v99
	v_mul_f32_e32 v0, v0, v96
	v_mul_f32_e32 v1, v1, v97
	v_mul_f32_e32 v20, v20, v124
	v_mul_f32_e32 v21, v21, v125
	v_mul_f32_e32 v18, v18, v126
	v_mul_f32_e32 v19, v19, v127
	v_mul_f32_e32 v16, v16, v124
	v_mul_f32_e32 v17, v17, v125
	v_mul_f32_e32 v14, v14, v98
	v_mul_f32_e32 v15, v15, v99
	v_mul_f32_e32 v12, v12, v96
	v_mul_f32_e32 v13, v13, v97
	v_mfma_f32_16x16x32_bf16 v[8:11], v[112:115], v[88:91], v[6:9]
	v_mfma_f32_16x16x32_bf16 v[4:7], v[112:115], v[92:95], v[0:3]
	s_nop 2
	v_mul_f32_e64 v2, v66, v98
	v_mul_f32_e64 v3, v67, v99
	v_mul_f32_e32 v0, v64, v96
	v_mul_f32_e32 v1, v65, v97
	v_mfma_f32_16x16x32_bf16 v[44:47], v[100:103], v[84:87], v[44:47]
	v_subrev_u32_e32 v64, 47, v185
	v_mfma_f32_16x16x32_bf16 v[40:43], v[100:103], v[88:91], v[40:43]
	v_mfma_f32_16x16x32_bf16 v[36:39], v[100:103], v[92:95], v[36:39]
	v_mfma_f32_16x16x32_bf16 v[32:35], v[100:103], v[108:111], v[32:35]
	v_mfma_f32_16x16x32_bf16 v[28:31], v[104:107], v[84:87], v[28:31]
	v_mfma_f32_16x16x32_bf16 v[24:27], v[104:107], v[88:91], v[24:27]
	v_mfma_f32_16x16x32_bf16 v[20:23], v[104:107], v[92:95], v[20:23]
	v_mfma_f32_16x16x32_bf16 v[16:19], v[104:107], v[108:111], v[16:19]
	v_mfma_f32_16x16x32_bf16 v[12:15], v[112:115], v[84:87], v[12:15]
	v_mfma_f32_16x16x32_bf16 v[0:3], v[112:115], v[108:111], v[0:3]
	s_and_saveexec_b64 s[52:53], s[38:39]
	s_cbranch_execz .LBB0_464
	v_or_b32_e32 v65, 16, v184
	s_cmp_gt_u32 s9, 15
	s_mov_b64 vcc, -1
	s_cbranch_scc0 .LBB0_716
	v_sub_u32_e32 v64, 0x9ff, v65
	s_mov_b64 vcc, 0
